# adds NSA selected-branch flash loop: five P.V V-fragment LDS reads issued right after the QK^T MFMAs (land during softmax)
# speedup vs baseline: 1.0144x; 1.0017x over previous
; DI int crow(int reg, int h) { return (reg & 3) + 8 * (reg >> 2) + 4 * h; }
; #define MFMA32(a, b, c) __builtin_amdgcn_mfma_f32_32x32x16_bf16((a), (b), (c), 0, 0, 0)
; template <int MODE>
; DI void nsa_flash(const bf16_t* kbase, const bf16_t* vbase, int j0, int j1, int t, unsigned selmask, const bf16x8 (&qf)[4],
;                   f32x16 (&o)[2], float& lsum, bf16_t* Ks, bf16_t* VTs, int tid, int r, int hh) {
;     ...
;   for (int j = j0; j <= j1; ++j) {
;     __syncthreads();
;     *(u32x4*)(Ks + kkey * 72 + kdc * 8) = kreg;
; #pragma unroll
;     for (int e = 0; e < 4; ++e) { VTs[(dc * 8 + 2 * e) * 136 + key] = (bf16_t)(vreg[e] & 0xffffu); VTs[(dc * 8 + 2 * e + 1) * 136 + key] = (bf16_t)(vreg[e] >> 16); }
;     __syncthreads();
;     if (j < j1) { kreg = *(const u32x4*)(kbase + (size_t)((j + 1) * 64 + kkey) * LDP0 + kdc * 8); vreg = *(const u32x4*)(vbase + (size_t)((j + 1) * 64 + key) * LDP0 + dc * 8); }
;     const bool rowsel = (MODE == 1) ? (((selmask >> j) & 1u) != 0u) : true;
;     const bool needmask = (j == j1) || (MODE == 2 && j + 8 == j1);
;     f32x16 x[2]; float mx = NEGF;
; #pragma unroll
;     for (int sub = 0; sub < 2; ++sub) { x[sub] = zero16();
; #pragma unroll
;       for (int kk = 0; kk < 4; ++kk) x[sub] = MFMA32(*(const bf16x8*)(Ks + (sub * 32 + r) * 72 + kk * 16 + 8 * hh), qf[kk], x[sub]); }
;     if (needmask) {
; #pragma unroll
;       for (int sub = 0; sub < 2; ++sub)
; #pragma unroll
;         for (int i = 0; i < 16; ++i) { const int kp = j * 64 + sub * 32 + crow(i, hh);
;           bool ok = (kp <= t); if (MODE == 2) ok = ok && (t - kp < 512);
;           x[sub][i] = ok ? x[sub][i] : NEGF; }
;     }
; #pragma unroll
;     for (int sub = 0; sub < 2; ++sub)
; #pragma unroll
;       for (int i = 0; i < 16; ++i) mx = fmaxf(mx, x[sub][i]);
;     mx = fmaxf(mx, __shfl_xor(mx, 32));
;     mx = rowsel ? fmaxf(m, mx) : m;
;     const float alpha = __builtin_amdgcn_exp2f(m - mx); m = mx;
.LBB0_628:
	v_readlane_b32 s2, v252, 56
	v_readlane_b32 s3, v252, 57
	s_or_b64 exec, exec, s[2:3]
	v_mul_u32_u24_e32 v0, 0xb80000, v85
	v_readlane_b32 s2, v252, 40
	v_lshlrev_b32_e32 v0, 1, v0
	v_mov_b32_e32 v1, v169
	v_readlane_b32 s3, v252, 41
	v_and_b32_e32 v120, 63, v84
	v_mul_u32_u24_e32 v6, 0x1700, v120
	v_lshl_add_u64 v[90:91], s[2:3], 0, v[0:1]
	v_lshlrev_b32_e32 v0, 7, v107
	v_lshl_add_u64 v[2:3], v[90:91], 0, v[0:1]
	s_mov_b64 s[2:3], 0x2420
	v_lshl_add_u64 v[0:1], v[2:3], 0, s[2:3]
	s_mov_b64 s[2:3], 0x2620
	v_lshl_add_u64 v[2:3], v[2:3], 0, s[2:3]
	v_mad_i64_i32 v[4:5], s[2:3], v106, s97, v[0:1]
	v_lshlrev_b32_e32 v6, 1, v6
	v_mov_b32_e32 v7, v169
	v_and_b32_e32 v92, -8, v106
	v_lshl_add_u64 v[4:5], v[4:5], 0, v[168:169]
	v_lshl_add_u64 v[6:7], v[2:3], 0, v[6:7]
	v_ashrrev_i32_e32 v93, 31, v92
	s_waitcnt lgkmcnt(0)
	s_barrier
	v_lshl_add_u64 v[6:7], v[92:93], 1, v[6:7]
	global_load_dwordx4 v[84:87], v[4:5], off
	global_load_dwordx4 v[80:83], v[6:7], off
	v_lshl_add_u32 v4, v109, 2, 32
	v_add_u32_e32 v4, 0x10c00, v4
	ds_read_b32 v122, v4
	s_movk_i32 s2, 0x88
	v_mul_lo_u32 v4, v92, s2
	v_lshl_add_u32 v123, v120, 1, 32
	v_lshlrev_b32_e32 v5, 1, v4
	v_lshlrev_b32_e32 v124, 1, v120
	v_add3_u32 v125, 32, v94, v168
	v_cmp_ne_u32_e32 vcc, 31, v108
	v_or_b32_e32 v115, 64, v120
	v_add_u32_e32 v116, 64, v106
	v_add_u32_e32 v117, v123, v5
	v_add3_u32 v118, 32, v5, v124
	v_add_u32_e32 v128, 0x110, v4
	v_add_u32_e32 v127, 0x220, v4
	v_add_u32_e32 v126, 0x330, v4
	s_and_saveexec_b64 s[2:3], vcc
	s_xor_b64 s[8:9], exec, s[2:3]
	s_cbranch_execz .LBB0_632
	v_mov_b32_e32 v121, 0
	v_lshl_add_u64 v[94:95], v[0:1], 0, v[168:169]
	v_lshl_add_u64 v[96:97], v[92:93], 1, v[2:3]
	v_add_u32_e32 v128, 0x110, v4
	v_add_u32_e32 v127, 0x220, v4
	v_add_u32_e32 v126, 0x330, v4
	s_mov_b32 s2, 0
	v_mov_b32_e32 v132, 0xf149f2ca
	s_mov_b64 s[10:11], 0
	v_mov_b32_e32 v130, v116
	v_mov_b32_e32 v131, v115
	v_mov_b32_e32 v0, 0
	v_mov_b32_e32 v1, v121
	v_mov_b32_e32 v2, v121
	v_mov_b32_e32 v3, v121
	v_mov_b32_e32 v4, v121
	v_mov_b32_e32 v5, v121
	v_mov_b32_e32 v6, v121
	v_mov_b32_e32 v7, v121
	v_mov_b32_e32 v8, v121
	v_mov_b32_e32 v9, v121
	v_mov_b32_e32 v10, v121
	v_mov_b32_e32 v11, v121
	v_mov_b32_e32 v12, v121
	v_mov_b32_e32 v13, v121
	v_mov_b32_e32 v14, v121
	v_mov_b32_e32 v15, v121
	v_mov_b32_e32 v16, 0
	v_mov_b32_e32 v17, v121
	v_mov_b32_e32 v18, v121
	v_mov_b32_e32 v19, v121
	v_mov_b32_e32 v20, v121
	v_mov_b32_e32 v21, v121
	v_mov_b32_e32 v22, v121
	v_mov_b32_e32 v23, v121
	v_mov_b32_e32 v24, v121
	v_mov_b32_e32 v25, v121
	v_mov_b32_e32 v26, v121
	v_mov_b32_e32 v27, v121
	v_mov_b32_e32 v28, v121
	v_mov_b32_e32 v29, v121
	v_mov_b32_e32 v30, v121
	v_mov_b32_e32 v31, v121
	s_mov_b32 s3, 0xf149f2ca
	s_mov_b32 s12, 0xefa18f08
	v_add_u32_e32 v250, v112, v113
	v_add_u32_e32 v251, 0x6800, v250
	v_add_u32_e32 v250, 0x4800, v250
.LBB0_630:
	v_mad_i64_i32 v[32:33], s[4:5], v130, s97, v[94:95]
	v_mov_b32_e32 v133, v121
	s_waitcnt lgkmcnt(0)
	s_barrier
	s_waitcnt vmcnt(1)
	ds_write_b128 v125, v[84:87]
	s_waitcnt vmcnt(0)
	ds_write_b16 v117, v80 offset:18432
	ds_write_b16_d16_hi v118, v80 offset:18704
	ds_write_b16 v117, v81 offset:18976
	ds_write_b16_d16_hi v118, v81 offset:19248
	ds_write_b16 v117, v82 offset:19520
	ds_write_b16_d16_hi v118, v82 offset:19792
	ds_write_b16 v117, v83 offset:20064
	ds_write_b16_d16_hi v118, v83 offset:20336
	s_waitcnt lgkmcnt(0)
	s_barrier
	global_load_dwordx4 v[84:87], v[32:33], off
	v_mad_i64_i32 v[32:33], s[4:5], v131, s97, v[96:97]
	v_add_u32_e32 v121, v111, v114
	global_load_dwordx4 v[80:83], v[32:33], off
	ds_read_b128 v[32:35], v121
	ds_read_b128 v[36:39], v121 offset:32
	s_waitcnt lgkmcnt(1)
	v_mfma_f32_32x32x16_bf16 v[48:63], v[32:35], v[64:67], 0
	ds_read_b128 v[32:35], v121 offset:64
	ds_read_b128 v[134:137], v121 offset:4640
	v_add_u32_e32 v131, 64, v131
	v_add_u32_e32 v130, 64, v130
	s_waitcnt lgkmcnt(2)
	v_mfma_f32_32x32x16_bf16 v[48:63], v[36:39], v[68:71], v[48:63]
	s_waitcnt lgkmcnt(1)
	v_mfma_f32_32x32x16_bf16 v[48:63], v[32:35], v[72:75], v[48:63]
	ds_read_b128 v[32:35], v121 offset:96
	s_waitcnt lgkmcnt(0)
	v_mfma_f32_32x32x16_bf16 v[48:63], v[32:35], v[76:79], v[48:63]
	ds_read_b128 v[32:35], v121 offset:4608
	s_waitcnt lgkmcnt(0)
	v_mfma_f32_32x32x16_bf16 v[32:47], v[32:35], v[64:67], 0
	v_mfma_f32_32x32x16_bf16 v[32:47], v[134:137], v[68:71], v[32:47]
	ds_read_b128 v[134:137], v121 offset:4672
	s_waitcnt lgkmcnt(0)
	v_mfma_f32_32x32x16_bf16 v[32:47], v[134:137], v[72:75], v[32:47]
	ds_read_b128 v[134:137], v121 offset:4704
	v_lshrrev_b32_e32 v121, s2, v122
	v_and_b32_e32 v121, 1, v121
	v_cmp_eq_u32_e32 vcc, 1, v121
	s_nop 0
	v_max3_f32 v121, v48, s3, v49
	v_max3_f32 v121, v121, v50, v51
	v_max3_f32 v121, v121, v52, v53
	s_waitcnt lgkmcnt(0)
	v_mfma_f32_32x32x16_bf16 v[32:47], v[134:137], v[76:79], v[32:47]
	ds_read2_b64 v[228:231], v251 offset0:64 offset1:66
	ds_read2_b64 v[232:235], v251 offset0:68 offset1:70
	ds_read2_b64 v[236:239], v250 offset0:8 offset1:10
	ds_read2_b64 v[240:243], v251 offset0:72 offset1:74
	ds_read2_b64 v[244:247], v250 offset0:12 offset1:14
	v_max3_f32 v121, v121, v54, v55
	v_max3_f32 v121, v121, v56, v57
	v_max3_f32 v121, v121, v58, v59
	v_max3_f32 v121, v121, v60, v61
	v_max3_f32 v121, v121, v62, v63
	s_add_i32 s2, s2, 1
	s_nop 5
	v_max3_f32 v121, v121, v32, v33
	v_max3_f32 v121, v121, v34, v35
	v_max3_f32 v121, v121, v36, v37
	v_max3_f32 v121, v121, v38, v39
	v_max3_f32 v121, v121, v40, v41
	v_max3_f32 v121, v121, v42, v43
	v_max3_f32 v121, v121, v44, v45
	v_max3_f32 v121, v121, v46, v47
	ds_bpermute_b32 v129, v102, v121
	s_waitcnt lgkmcnt(0)
; #define MFMA32(a, b, c) __builtin_amdgcn_mfma_f32_32x32x16_bf16((a), (b), (c), 0, 0, 0)
; template <int MODE>
; DI void nsa_flash(const bf16_t* kbase, const bf16_t* vbase, int j0, int j1, int t, unsigned selmask, const bf16x8 (&qf)[4],
;                   f32x16 (&o)[2], float& lsum, bf16_t* Ks, bf16_t* VTs, int tid, int r, int hh) {
;     ...
;     const float alpha = __builtin_amdgcn_exp2f(m - mx); m = mx;
;     const float mexp = (rowsel && mx > -1e29f) ? mx : 1e30f;
;     float ps = 0.f;
; #pragma unroll
;     for (int sub = 0; sub < 2; ++sub)
; #pragma unroll
;       for (int i = 0; i < 16; ++i) { const float pv = __builtin_amdgcn_exp2f(x[sub][i] - mexp); x[sub][i] = pv; ps += pv; }
;     ps += __shfl_xor(ps, 32);
;     lsum = lsum * alpha + ps;
; #pragma unroll
;     for (int i = 0; i < 16; ++i) { o[0][i] *= alpha; o[1][i] *= alpha; }
; #pragma unroll
;     for (int sub = 0; sub < 2; ++sub)
; #pragma unroll
;       for (int s2 = 0; s2 < 2; ++s2) {
;         const bf16x8 pb = pack8(x[sub][8 * s2], x[sub][8 * s2 + 1], x[sub][8 * s2 + 2], x[sub][8 * s2 + 3], x[sub][8 * s2 + 4], x[sub][8 * s2 + 5], x[sub][8 * s2 + 6], x[sub][8 * s2 + 7]);
; #pragma unroll
;         for (int dt = 0; dt < 2; ++dt) { const bf16_t* vp = VTs + (dt * 32 + r) * 136 + sub * 32 + 16 * s2 + 4 * hh;
;           const s16x4 lo = *(const s16x4*)vp, hi = *(const s16x4*)(vp + 8);
;           const bf16x8 va = __builtin_shufflevector(lo, hi, 0, 1, 2, 3, 4, 5, 6, 7);
;           o[dt] = MFMA32(va, pb, o[dt]); } }
	v_max3_f32 v121, v132, v121, v129
	v_cndmask_b32_e32 v129, v132, v121, vcc
	v_cmp_lt_f32_e64 s[6:7], s12, v129
	s_and_b64 vcc, vcc, s[6:7]
	v_cndmask_b32_e32 v121, v202, v121, vcc
	v_sub_f32_e32 v48, v48, v121
	v_exp_f32_e32 v134, v48
	v_sub_f32_e32 v49, v49, v121
	v_exp_f32_e32 v135, v49
	v_sub_f32_e32 v49, v50, v121
	v_exp_f32_e32 v136, v49
	v_sub_f32_e32 v49, v51, v121
	v_exp_f32_e32 v137, v49
	v_sub_f32_e32 v49, v52, v121
	v_add_f32_e32 v48, 0, v134
	v_exp_f32_e32 v138, v49
	v_sub_f32_e32 v49, v53, v121
	v_add_f32_e32 v48, v135, v48
	v_exp_f32_e32 v139, v49
	v_sub_f32_e32 v49, v54, v121
	v_add_f32_e32 v48, v136, v48
	v_exp_f32_e32 v140, v49
	v_sub_f32_e32 v49, v55, v121
	v_add_f32_e32 v48, v137, v48
	v_exp_f32_e32 v141, v49
	v_add_f32_e32 v48, v138, v48
	v_add_f32_e32 v48, v139, v48
	v_add_f32_e32 v48, v140, v48
	v_add_f32_e32 v49, v141, v48
	v_sub_f32_e32 v48, v56, v121
	v_exp_f32_e32 v48, v48
	v_sub_f32_e32 v56, v63, v121
	v_exp_f32_e32 v56, v56
	v_sub_f32_e32 v32, v32, v121
	v_add_f32_e32 v50, v48, v49
	v_sub_f32_e32 v49, v57, v121
	v_exp_f32_e32 v49, v49
	v_sub_f32_e32 v33, v33, v121
	v_sub_f32_e32 v132, v132, v129
	v_cmp_eq_u32_e32 vcc, s2, v100
	v_add_f32_e32 v51, v49, v50
	v_sub_f32_e32 v50, v58, v121
	v_exp_f32_e32 v50, v50
	s_or_b64 s[10:11], vcc, s[10:11]
	v_add_f32_e32 v52, v50, v51
	v_sub_f32_e32 v51, v59, v121
	v_exp_f32_e32 v51, v51
	s_nop 0
	v_add_f32_e32 v53, v51, v52
	v_sub_f32_e32 v52, v60, v121
	v_exp_f32_e32 v52, v52
	s_nop 0
	v_add_f32_e32 v54, v52, v53
	v_sub_f32_e32 v53, v61, v121
	v_exp_f32_e32 v53, v53
	s_nop 0
	v_add_f32_e32 v55, v53, v54
	v_sub_f32_e32 v54, v62, v121
	v_exp_f32_e32 v54, v54
	s_nop 0
	v_add_f32_e32 v55, v54, v55
	v_add_f32_e32 v57, v56, v55
	v_exp_f32_e32 v55, v32
	s_nop 0
	v_add_f32_e32 v32, v55, v57
	v_exp_f32_e32 v57, v33
	v_sub_f32_e32 v33, v34, v121
	v_exp_f32_e32 v58, v33
	v_sub_f32_e32 v33, v35, v121
	v_exp_f32_e32 v59, v33
	v_sub_f32_e32 v33, v36, v121
	v_exp_f32_e32 v36, v33
	v_sub_f32_e32 v33, v37, v121
	v_add_f32_e32 v32, v57, v32
	v_exp_f32_e32 v37, v33
	v_sub_f32_e32 v33, v38, v121
	v_add_f32_e32 v32, v58, v32
	v_exp_f32_e32 v38, v33
	v_sub_f32_e32 v33, v39, v121
	v_add_f32_e32 v32, v59, v32
	v_exp_f32_e32 v60, v33
	v_sub_f32_e32 v33, v40, v121
	v_add_f32_e32 v32, v36, v32
	v_exp_f32_e32 v39, v33
	v_sub_f32_e32 v33, v41, v121
	v_add_f32_e32 v32, v37, v32
	v_exp_f32_e32 v40, v33
	v_sub_f32_e32 v33, v42, v121
	v_add_f32_e32 v32, v38, v32
	v_exp_f32_e32 v41, v33
	v_sub_f32_e32 v33, v43, v121
	v_add_f32_e32 v32, v60, v32
	v_exp_f32_e32 v42, v33
	v_sub_f32_e32 v33, v44, v121
	v_add_f32_e32 v32, v39, v32
	v_exp_f32_e32 v43, v33
	v_sub_f32_e32 v33, v45, v121
	v_add_f32_e32 v32, v40, v32
	v_exp_f32_e32 v44, v33
	v_sub_f32_e32 v33, v46, v121
	v_add_f32_e32 v32, v41, v32
	v_exp_f32_e32 v45, v33
	v_sub_f32_e32 v33, v47, v121
	v_add_f32_e32 v32, v42, v32
	v_exp_f32_e32 v46, v33
	v_add_f32_e32 v32, v43, v32
	v_add_f32_e32 v32, v44, v32
	v_add_f32_e32 v32, v45, v32
	v_add_f32_e32 v33, v46, v32
	ds_bpermute_b32 v34, v102, v33
	v_exp_f32_e32 v32, v132
	v_add_u32_e32 v47, v112, v113
	v_add_u32_e32 v61, 0x4800, v47
	v_cvt_pk_bf16_f32 v35, v140, v141
	s_waitcnt lgkmcnt(0)
	v_add_f32_e32 v121, v33, v34
	v_fmac_f32_e32 v121, v133, v32
	v_pk_mul_f32 v[0:1], v[0:1], v[32:33] op_sel_hi:[1,0]
	v_pk_mul_f32 v[16:17], v[16:17], v[32:33] op_sel_hi:[1,0]
	v_pk_mul_f32 v[2:3], v[2:3], v[32:33] op_sel_hi:[1,0]
	v_pk_mul_f32 v[18:19], v[18:19], v[32:33] op_sel_hi:[1,0]
	v_pk_mul_f32 v[4:5], v[4:5], v[32:33] op_sel_hi:[1,0]
	v_pk_mul_f32 v[20:21], v[20:21], v[32:33] op_sel_hi:[1,0]
	v_pk_mul_f32 v[6:7], v[6:7], v[32:33] op_sel_hi:[1,0]
	v_pk_mul_f32 v[22:23], v[22:23], v[32:33] op_sel_hi:[1,0]
	v_pk_mul_f32 v[8:9], v[8:9], v[32:33] op_sel_hi:[1,0]
	v_pk_mul_f32 v[24:25], v[24:25], v[32:33] op_sel_hi:[1,0]
	v_pk_mul_f32 v[10:11], v[10:11], v[32:33] op_sel_hi:[1,0]
	v_pk_mul_f32 v[26:27], v[26:27], v[32:33] op_sel_hi:[1,0]
	v_pk_mul_f32 v[12:13], v[12:13], v[32:33] op_sel_hi:[1,0]
	v_pk_mul_f32 v[28:29], v[28:29], v[32:33] op_sel_hi:[1,0]
	v_pk_mul_f32 v[14:15], v[14:15], v[32:33] op_sel_hi:[1,0]
	v_pk_mul_f32 v[30:31], v[30:31], v[32:33] op_sel_hi:[1,0]
	v_cvt_pk_bf16_f32 v32, v134, v135
	v_cvt_pk_bf16_f32 v33, v136, v137
	v_cvt_pk_bf16_f32 v34, v138, v139
	ds_read2_b64 v[132:135], v61 offset1:2
	ds_read2_b64 v[136:139], v61 offset0:4 offset1:6
	v_add_u32_e32 v47, 0x6800, v47
	s_waitcnt lgkmcnt(1)
	v_mfma_f32_32x32x16_bf16 v[0:15], v[132:135], v[32:35], v[0:15]
	s_waitcnt lgkmcnt(0)
	v_mfma_f32_32x32x16_bf16 v[16:31], v[228:231], v[32:35], v[16:31]
	v_cvt_pk_bf16_f32 v32, v48, v49
	v_cvt_pk_bf16_f32 v33, v50, v51
	v_cvt_pk_bf16_f32 v34, v52, v53
	v_cvt_pk_bf16_f32 v35, v54, v56
	v_mov_b32_e32 v132, v129
	s_waitcnt lgkmcnt(0)
	v_mfma_f32_32x32x16_bf16 v[16:31], v[232:235], v[32:35], v[16:31]
	v_mfma_f32_32x32x16_bf16 v[0:15], v[136:139], v[32:35], v[0:15]
	v_cvt_pk_bf16_f32 v32, v55, v57
	v_cvt_pk_bf16_f32 v33, v58, v59
	v_cvt_pk_bf16_f32 v34, v36, v37
	v_cvt_pk_bf16_f32 v35, v38, v60
	s_waitcnt lgkmcnt(0)
	s_nop 0
	v_mfma_f32_32x32x16_bf16 v[0:15], v[236:239], v[32:35], v[0:15]
	s_waitcnt lgkmcnt(0)
	v_mfma_f32_32x32x16_bf16 v[16:31], v[240:243], v[32:35], v[16:31]
	v_cvt_pk_bf16_f32 v32, v39, v40
	v_cvt_pk_bf16_f32 v33, v41, v42
	v_cvt_pk_bf16_f32 v34, v43, v44
	v_cvt_pk_bf16_f32 v35, v45, v46
	s_waitcnt lgkmcnt(0)
	s_nop 0
	v_mfma_f32_32x32x16_bf16 v[0:15], v[244:247], v[32:35], v[0:15]
	ds_read2_b64 v[36:39], v47 offset0:76 offset1:78
	s_waitcnt lgkmcnt(0)
	v_mfma_f32_32x32x16_bf16 v[16:31], v[36:39], v[32:35], v[16:31]
	s_andn2_b64 exec, exec, s[10:11]
	s_cbranch_execnz .LBB0_630
	s_mov_b32 s90, 0xefa18f08
	s_or_b64 exec, exec, s[10:11]
